# phase 10 GEMM on the phase-1 256x128 big-tile K-loop (all blocks, at the start of the phase); hipcc's 128x128 loop skipped on the 512-block grid
# speedup vs baseline: 1.0106x; 1.0048x over previous
.LBB0_763:
	s_or_b64 exec, exec, s[0:1]
	s_mov_b32 s91, 0
	s_cmp_lg_u32 s96, 0x200
	s_cbranch_scc1 .Lq10_skip
	v_lshrrev_b32_e32 v236, 3, v199
	v_lshrrev_b32_e32 v237, 4, v199
	v_xor_b32_e32 v237, v237, v199
	v_and_b32_e32 v237, 7, v237
	v_lshlrev_b32_e32 v237, 4, v237
	v_lshl_add_u32 v192, v236, 12, v237
	v_add_u32_e32 v193, 0x20000, v192
	v_add_u32_e32 v194, 0x40000, v192
	v_add_u32_e32 v195, 0x60000, v192
	v_and_b32_e32 v236, 15, v199
	v_bfe_u32 v237, v199, 4, 2
	v_lshrrev_b32_e32 v238, 1, v236
	v_lshlrev_b32_e32 v202, 3, v237
	v_xor_b32_e32 v237, v237, v238
	v_lshlrev_b32_e32 v237, 4, v237
	v_xor_b32_e32 v238, 64, v237
	v_lshrrev_b32_e32 v201, 7, v199
	v_lshl_add_u32 v201, v201, 7, v236
	v_lshlrev_b32_e32 v196, 7, v201
	v_bfe_u32 v198, v199, 6, 1
	v_lshl_add_u32 v202, v198, 7, v202
	v_lshl_add_u32 v198, v198, 6, v236
	v_lshlrev_b32_e32 v198, 7, v198
	v_add_u32_e32 v198, 0x8000, v198
	v_add_u32_e32 v197, v196, v238
	v_add_u32_e32 v243, v198, v238
	v_add_u32_e32 v196, v196, v237
	v_add_u32_e32 v198, v198, v237
	v_lshrrev_b32_e32 v236, 6, v199
	v_lshlrev_b32_e32 v236, 10, v236
	s_nop 0
	v_readfirstlane_b32 s32, v236
	v_lshrrev_b32_e32 v240, 6, v199
	v_mul_u32_u24_e32 v240, 0x900, v240
	v_add_u32_e32 v240, 0xc000, v240
	v_and_b32_e32 v241, 15, v199
	v_mul_u32_u24_e32 v241, 0x90, v241
	v_bfe_u32 v238, v199, 4, 2
	v_lshl_add_u32 v241, v238, 3, v241
	v_add_u32_e32 v236, v240, v241
	v_and_b32_e32 v241, 63, v199
	v_lshrrev_b32_e32 v238, 3, v241
	v_mul_u32_u24_e32 v238, 0x90, v238
	v_and_b32_e32 v241, 7, v241
	v_lshl_add_u32 v238, v241, 4, v238
	v_add_u32_e32 v237, v240, v238
	v_readlane_b32 s90, v242, 45
	s_and_b32 s51, s90, 63
	s_lshl_b32 s51, s51, 20
	s_add_u32 s36, s94, s51
	s_addc_u32 s37, s95, 0
	s_add_u32 s36, s36, 0x15000000
	s_addc_u32 s37, s37, 0
	s_lshr_b32 s51, s90, 6
	s_lshl_b32 s51, s51, 19
	s_add_u32 s44, s94, s51
	s_addc_u32 s45, s95, 0
	s_add_u32 s44, s44, 0x1c200000
	s_addc_u32 s45, s45, 0
	s_add_u32 s40, s36, 0x80000
	s_addc_u32 s41, s37, 0
	s_and_b32 s21, s90, 31
	s_mov_b32 s20, s21
	s_lshl_b32 s51, s21, 7
	s_add_u32 s36, s36, s51
	s_addc_u32 s37, s37, 0
	s_add_u32 s40, s40, s51
	s_addc_u32 s41, s41, 0
	s_add_u32 s44, s44, s51
	s_addc_u32 s45, s45, 0
	s_barrier
	s_add_u32 m0, s32, 0x0
	s_nop 0
	global_load_lds_dwordx4 v192, s[36:37]
	s_add_u32 m0, s32, 0x1000
	s_nop 0
	global_load_lds_dwordx4 v193, s[36:37]
	s_add_u32 m0, s32, 0x2000
	s_nop 0
	global_load_lds_dwordx4 v194, s[36:37]
	s_add_u32 m0, s32, 0x3000
	s_nop 0
	global_load_lds_dwordx4 v195, s[36:37]
	s_add_u32 m0, s32, 0x4000
	s_nop 0
	global_load_lds_dwordx4 v192, s[40:41]
	s_add_u32 m0, s32, 0x5000
	s_nop 0
	global_load_lds_dwordx4 v193, s[40:41]
	s_add_u32 m0, s32, 0x6000
	s_nop 0
	global_load_lds_dwordx4 v194, s[40:41]
	s_add_u32 m0, s32, 0x7000
	s_nop 0
	global_load_lds_dwordx4 v195, s[40:41]
	s_add_u32 m0, s32, 0x8000
	s_nop 0
	global_load_lds_dwordx4 v192, s[44:45]
	s_add_u32 m0, s32, 0x9000
	s_nop 0
	global_load_lds_dwordx4 v193, s[44:45]
	s_add_u32 m0, s32, 0xa000
	s_nop 0
	global_load_lds_dwordx4 v194, s[44:45]
	s_add_u32 m0, s32, 0xb000
	s_nop 0
	global_load_lds_dwordx4 v195, s[44:45]
	s_add_u32 s36, s36, 0x80
	s_addc_u32 s37, s37, 0
	s_add_u32 s40, s40, 0x80
	s_addc_u32 s41, s41, 0
	s_add_u32 s44, s44, 0x80
	s_addc_u32 s45, s45, 0
	s_add_i32 s20, s20, 1
	s_cmp_eq_u32 s20, 32
	s_cbranch_scc1 .Lq10_wrap0

.Lq10_tile:
	s_add_u32 s91, s90, 0x200
	s_and_b32 s51, s91, 63
	s_lshl_b32 s51, s51, 20
	s_add_u32 s46, s94, s51
	s_addc_u32 s47, s95, 0
	s_add_u32 s46, s46, 0x15000000
	s_addc_u32 s47, s47, 0
	s_lshr_b32 s51, s91, 6
	s_lshl_b32 s51, s51, 19
	s_add_u32 s48, s94, s51
	s_addc_u32 s49, s95, 0
	s_add_u32 s48, s48, 0x1c200000
	s_addc_u32 s49, s49, 0
	s_lshl_b32 s51, s21, 7
	s_add_u32 s46, s46, s51
	s_addc_u32 s47, s47, 0
	s_add_u32 s48, s48, s51
	s_addc_u32 s49, s49, 0
	v_mov_b32_e32 v0, 0
	v_mov_b32_e32 v1, 0
	v_mov_b32_e32 v2, 0
	v_mov_b32_e32 v3, 0
	v_mov_b32_e32 v4, 0
	v_mov_b32_e32 v5, 0
	v_mov_b32_e32 v6, 0
	v_mov_b32_e32 v7, 0
	v_mov_b32_e32 v8, 0
	v_mov_b32_e32 v9, 0
	v_mov_b32_e32 v10, 0
	v_mov_b32_e32 v11, 0
	v_mov_b32_e32 v12, 0
	v_mov_b32_e32 v13, 0
	v_mov_b32_e32 v14, 0
	v_mov_b32_e32 v15, 0
	v_mov_b32_e32 v16, 0
	v_mov_b32_e32 v17, 0
	v_mov_b32_e32 v18, 0
	v_mov_b32_e32 v19, 0
	v_mov_b32_e32 v20, 0
	v_mov_b32_e32 v21, 0
	v_mov_b32_e32 v22, 0
	v_mov_b32_e32 v23, 0
	v_mov_b32_e32 v24, 0
	v_mov_b32_e32 v25, 0
	v_mov_b32_e32 v26, 0
	v_mov_b32_e32 v27, 0
	v_mov_b32_e32 v28, 0
	v_mov_b32_e32 v29, 0
	v_mov_b32_e32 v30, 0
	v_mov_b32_e32 v31, 0
	v_mov_b32_e32 v32, 0
	v_mov_b32_e32 v33, 0
	v_mov_b32_e32 v34, 0
	v_mov_b32_e32 v35, 0
	v_mov_b32_e32 v36, 0
	v_mov_b32_e32 v37, 0
	v_mov_b32_e32 v38, 0
	v_mov_b32_e32 v39, 0
	v_mov_b32_e32 v40, 0
	v_mov_b32_e32 v41, 0
	v_mov_b32_e32 v42, 0
	v_mov_b32_e32 v43, 0
	v_mov_b32_e32 v44, 0
	v_mov_b32_e32 v45, 0
	v_mov_b32_e32 v46, 0
	v_mov_b32_e32 v47, 0
	v_mov_b32_e32 v48, 0
	v_mov_b32_e32 v49, 0
	v_mov_b32_e32 v50, 0
	v_mov_b32_e32 v51, 0
	v_mov_b32_e32 v52, 0
	v_mov_b32_e32 v53, 0
	v_mov_b32_e32 v54, 0
	v_mov_b32_e32 v55, 0
	v_mov_b32_e32 v56, 0
	v_mov_b32_e32 v57, 0
	v_mov_b32_e32 v58, 0
	v_mov_b32_e32 v59, 0
	v_mov_b32_e32 v60, 0
	v_mov_b32_e32 v61, 0
	v_mov_b32_e32 v62, 0
	v_mov_b32_e32 v63, 0
	v_mov_b32_e32 v64, 0
	v_mov_b32_e32 v65, 0
	v_mov_b32_e32 v66, 0
	v_mov_b32_e32 v67, 0
	v_mov_b32_e32 v68, 0
	v_mov_b32_e32 v69, 0
	v_mov_b32_e32 v70, 0
	v_mov_b32_e32 v71, 0
	v_mov_b32_e32 v72, 0
	v_mov_b32_e32 v73, 0
	v_mov_b32_e32 v74, 0
	v_mov_b32_e32 v75, 0
	v_mov_b32_e32 v76, 0
	v_mov_b32_e32 v77, 0
	v_mov_b32_e32 v78, 0
	v_mov_b32_e32 v79, 0
	v_mov_b32_e32 v80, 0
	v_mov_b32_e32 v81, 0
	v_mov_b32_e32 v82, 0
	v_mov_b32_e32 v83, 0
	v_mov_b32_e32 v84, 0
	v_mov_b32_e32 v85, 0
	v_mov_b32_e32 v86, 0
	v_mov_b32_e32 v87, 0
	v_mov_b32_e32 v88, 0
	v_mov_b32_e32 v89, 0
	v_mov_b32_e32 v90, 0
	v_mov_b32_e32 v91, 0
	v_mov_b32_e32 v92, 0
	v_mov_b32_e32 v93, 0
	v_mov_b32_e32 v94, 0
	v_mov_b32_e32 v95, 0
	v_mov_b32_e32 v96, 0
	v_mov_b32_e32 v97, 0
	v_mov_b32_e32 v98, 0
	v_mov_b32_e32 v99, 0
	v_mov_b32_e32 v100, 0
	v_mov_b32_e32 v101, 0
	v_mov_b32_e32 v102, 0
	v_mov_b32_e32 v103, 0
	v_mov_b32_e32 v104, 0
	v_mov_b32_e32 v105, 0
	v_mov_b32_e32 v106, 0
	v_mov_b32_e32 v107, 0
	v_mov_b32_e32 v108, 0
	v_mov_b32_e32 v109, 0
	v_mov_b32_e32 v110, 0
	v_mov_b32_e32 v111, 0
	v_mov_b32_e32 v112, 0
	v_mov_b32_e32 v113, 0
	v_mov_b32_e32 v114, 0
	v_mov_b32_e32 v115, 0
	v_mov_b32_e32 v116, 0
	v_mov_b32_e32 v117, 0
	v_mov_b32_e32 v118, 0
	v_mov_b32_e32 v119, 0
	v_mov_b32_e32 v120, 0
	v_mov_b32_e32 v121, 0
	v_mov_b32_e32 v122, 0
	v_mov_b32_e32 v123, 0
	v_mov_b32_e32 v124, 0
	v_mov_b32_e32 v125, 0
	v_mov_b32_e32 v126, 0
	v_mov_b32_e32 v127, 0
	s_mov_b32 s50, 0
	s_waitcnt vmcnt(32)
	s_branch .Lq10_k_in

.Lq10_k_in:
	s_barrier
	ds_read_b128 v[160:163], v198 offset:0
	ds_read_b128 v[164:167], v198 offset:2048
	ds_read_b128 v[168:171], v198 offset:4096
	ds_read_b128 v[172:175], v198 offset:6144
	ds_read_b128 v[128:131], v196 offset:0
	ds_read_b128 v[132:135], v196 offset:2048
	ds_read_b128 v[136:139], v196 offset:4096
	ds_read_b128 v[140:143], v196 offset:6144
	ds_read_b128 v[144:147], v196 offset:8192
	ds_read_b128 v[148:151], v196 offset:10240
	ds_read_b128 v[152:155], v196 offset:12288
	ds_read_b128 v[156:159], v196 offset:14336
	ds_read_b128 v[176:179], v243 offset:0
	ds_read_b128 v[180:183], v243 offset:2048
	ds_read_b128 v[184:187], v243 offset:4096
	ds_read_b128 v[188:191], v243 offset:6144
	ds_read_b128 v[204:207], v197 offset:0
	ds_read_b128 v[208:211], v197 offset:2048
	ds_read_b128 v[212:215], v197 offset:4096
	ds_read_b128 v[216:219], v197 offset:6144
	ds_read_b128 v[220:223], v197 offset:8192
	ds_read_b128 v[224:227], v197 offset:10240
	ds_read_b128 v[228:231], v197 offset:12288
	ds_read_b128 v[232:235], v197 offset:14336
	s_waitcnt lgkmcnt(12)
	s_setprio 1
	v_mfma_f32_16x16x32_bf16 v[0:3], v[160:163], v[128:131], v[0:3]
	v_mfma_f32_16x16x32_bf16 v[4:7], v[164:167], v[128:131], v[4:7]
	v_mfma_f32_16x16x32_bf16 v[8:11], v[168:171], v[128:131], v[8:11]
	v_mfma_f32_16x16x32_bf16 v[12:15], v[172:175], v[128:131], v[12:15]
	v_mfma_f32_16x16x32_bf16 v[16:19], v[160:163], v[132:135], v[16:19]
	v_mfma_f32_16x16x32_bf16 v[20:23], v[164:167], v[132:135], v[20:23]
	v_mfma_f32_16x16x32_bf16 v[24:27], v[168:171], v[132:135], v[24:27]
	v_mfma_f32_16x16x32_bf16 v[28:31], v[172:175], v[132:135], v[28:31]
	v_mfma_f32_16x16x32_bf16 v[32:35], v[160:163], v[136:139], v[32:35]
	v_mfma_f32_16x16x32_bf16 v[36:39], v[164:167], v[136:139], v[36:39]
	v_mfma_f32_16x16x32_bf16 v[40:43], v[168:171], v[136:139], v[40:43]
	v_mfma_f32_16x16x32_bf16 v[44:47], v[172:175], v[136:139], v[44:47]
	v_mfma_f32_16x16x32_bf16 v[48:51], v[160:163], v[140:143], v[48:51]
	v_mfma_f32_16x16x32_bf16 v[52:55], v[164:167], v[140:143], v[52:55]
	v_mfma_f32_16x16x32_bf16 v[56:59], v[168:171], v[140:143], v[56:59]
	v_mfma_f32_16x16x32_bf16 v[60:63], v[172:175], v[140:143], v[60:63]
	v_mfma_f32_16x16x32_bf16 v[64:67], v[160:163], v[144:147], v[64:67]
	v_mfma_f32_16x16x32_bf16 v[68:71], v[164:167], v[144:147], v[68:71]
	v_mfma_f32_16x16x32_bf16 v[72:75], v[168:171], v[144:147], v[72:75]
	v_mfma_f32_16x16x32_bf16 v[76:79], v[172:175], v[144:147], v[76:79]
	v_mfma_f32_16x16x32_bf16 v[80:83], v[160:163], v[148:151], v[80:83]
	v_mfma_f32_16x16x32_bf16 v[84:87], v[164:167], v[148:151], v[84:87]
	v_mfma_f32_16x16x32_bf16 v[88:91], v[168:171], v[148:151], v[88:91]
	v_mfma_f32_16x16x32_bf16 v[92:95], v[172:175], v[148:151], v[92:95]
	v_mfma_f32_16x16x32_bf16 v[96:99], v[160:163], v[152:155], v[96:99]
	v_mfma_f32_16x16x32_bf16 v[100:103], v[164:167], v[152:155], v[100:103]
	v_mfma_f32_16x16x32_bf16 v[104:107], v[168:171], v[152:155], v[104:107]
	v_mfma_f32_16x16x32_bf16 v[108:111], v[172:175], v[152:155], v[108:111]
	v_mfma_f32_16x16x32_bf16 v[112:115], v[160:163], v[156:159], v[112:115]
	v_mfma_f32_16x16x32_bf16 v[116:119], v[164:167], v[156:159], v[116:119]
	v_mfma_f32_16x16x32_bf16 v[120:123], v[168:171], v[156:159], v[120:123]
	v_mfma_f32_16x16x32_bf16 v[124:127], v[172:175], v[156:159], v[124:127]
	s_setprio 0
	s_waitcnt lgkmcnt(0)
	s_barrier
	s_add_u32 m0, s32, 0x0
	s_nop 0
	global_load_lds_dwordx4 v192, s[36:37]
	s_add_u32 m0, s32, 0x1000
	s_nop 0
	global_load_lds_dwordx4 v193, s[36:37]
	s_add_u32 m0, s32, 0x2000
	s_nop 0
	global_load_lds_dwordx4 v194, s[36:37]
	s_add_u32 m0, s32, 0x3000
	s_nop 0
	global_load_lds_dwordx4 v195, s[36:37]
	s_add_u32 m0, s32, 0x4000
	s_nop 0
	global_load_lds_dwordx4 v192, s[40:41]
	s_add_u32 m0, s32, 0x5000
	s_nop 0
	global_load_lds_dwordx4 v193, s[40:41]
	s_add_u32 m0, s32, 0x6000
	s_nop 0
	global_load_lds_dwordx4 v194, s[40:41]
	s_add_u32 m0, s32, 0x7000
	s_nop 0
	global_load_lds_dwordx4 v195, s[40:41]
	s_add_u32 m0, s32, 0x8000
	s_nop 0
	global_load_lds_dwordx4 v192, s[44:45]
	s_add_u32 m0, s32, 0x9000
	s_nop 0
	global_load_lds_dwordx4 v193, s[44:45]
	s_add_u32 m0, s32, 0xa000
	s_nop 0
	global_load_lds_dwordx4 v194, s[44:45]
	s_add_u32 m0, s32, 0xb000
	s_nop 0
	global_load_lds_dwordx4 v195, s[44:45]
	s_add_u32 s36, s36, 0x80
	s_addc_u32 s37, s37, 0
	s_add_u32 s40, s40, 0x80
	s_addc_u32 s41, s41, 0
	s_add_u32 s44, s44, 0x80
	s_addc_u32 s45, s45, 0
	s_add_i32 s20, s20, 1
	s_cmp_eq_u32 s20, 32
	s_cbranch_scc1 .Lq10_wrap1
.Lq10_wrapret1:
	s_setprio 1
	v_mfma_f32_16x16x32_bf16 v[0:3], v[176:179], v[204:207], v[0:3]
	v_mfma_f32_16x16x32_bf16 v[4:7], v[180:183], v[204:207], v[4:7]
	v_mfma_f32_16x16x32_bf16 v[8:11], v[184:187], v[204:207], v[8:11]
	v_mfma_f32_16x16x32_bf16 v[12:15], v[188:191], v[204:207], v[12:15]
	v_mfma_f32_16x16x32_bf16 v[16:19], v[176:179], v[208:211], v[16:19]
	v_mfma_f32_16x16x32_bf16 v[20:23], v[180:183], v[208:211], v[20:23]
	v_mfma_f32_16x16x32_bf16 v[24:27], v[184:187], v[208:211], v[24:27]
	v_mfma_f32_16x16x32_bf16 v[28:31], v[188:191], v[208:211], v[28:31]
	v_mfma_f32_16x16x32_bf16 v[32:35], v[176:179], v[212:215], v[32:35]
	v_mfma_f32_16x16x32_bf16 v[36:39], v[180:183], v[212:215], v[36:39]
	v_mfma_f32_16x16x32_bf16 v[40:43], v[184:187], v[212:215], v[40:43]
	v_mfma_f32_16x16x32_bf16 v[44:47], v[188:191], v[212:215], v[44:47]
	v_mfma_f32_16x16x32_bf16 v[48:51], v[176:179], v[216:219], v[48:51]
	v_mfma_f32_16x16x32_bf16 v[52:55], v[180:183], v[216:219], v[52:55]
	v_mfma_f32_16x16x32_bf16 v[56:59], v[184:187], v[216:219], v[56:59]
	v_mfma_f32_16x16x32_bf16 v[60:63], v[188:191], v[216:219], v[60:63]
	v_mfma_f32_16x16x32_bf16 v[64:67], v[176:179], v[220:223], v[64:67]
	v_mfma_f32_16x16x32_bf16 v[68:71], v[180:183], v[220:223], v[68:71]
	v_mfma_f32_16x16x32_bf16 v[72:75], v[184:187], v[220:223], v[72:75]
	v_mfma_f32_16x16x32_bf16 v[76:79], v[188:191], v[220:223], v[76:79]
	v_mfma_f32_16x16x32_bf16 v[80:83], v[176:179], v[224:227], v[80:83]
	v_mfma_f32_16x16x32_bf16 v[84:87], v[180:183], v[224:227], v[84:87]
	v_mfma_f32_16x16x32_bf16 v[88:91], v[184:187], v[224:227], v[88:91]
	v_mfma_f32_16x16x32_bf16 v[92:95], v[188:191], v[224:227], v[92:95]
	v_mfma_f32_16x16x32_bf16 v[96:99], v[176:179], v[228:231], v[96:99]
	v_mfma_f32_16x16x32_bf16 v[100:103], v[180:183], v[228:231], v[100:103]
	v_mfma_f32_16x16x32_bf16 v[104:107], v[184:187], v[228:231], v[104:107]
	v_mfma_f32_16x16x32_bf16 v[108:111], v[188:191], v[228:231], v[108:111]
	v_mfma_f32_16x16x32_bf16 v[112:115], v[176:179], v[232:235], v[112:115]
	v_mfma_f32_16x16x32_bf16 v[116:119], v[180:183], v[232:235], v[116:119]
	v_mfma_f32_16x16x32_bf16 v[120:123], v[184:187], v[232:235], v[120:123]
	v_mfma_f32_16x16x32_bf16 v[124:127], v[188:191], v[232:235], v[124:127]
	s_setprio 0
	s_add_i32 s50, s50, 1
	s_cmp_lt_u32 s50, 31
	s_cbranch_scc1 .Lq10_k
	s_waitcnt vmcnt(0)
	s_barrier
	ds_read_b128 v[160:163], v198 offset:0
	ds_read_b128 v[164:167], v198 offset:2048
	ds_read_b128 v[168:171], v198 offset:4096
	ds_read_b128 v[172:175], v198 offset:6144
	ds_read_b128 v[128:131], v196 offset:0
	ds_read_b128 v[132:135], v196 offset:2048
	ds_read_b128 v[136:139], v196 offset:4096
	ds_read_b128 v[140:143], v196 offset:6144
	ds_read_b128 v[144:147], v196 offset:8192
	ds_read_b128 v[148:151], v196 offset:10240
	ds_read_b128 v[152:155], v196 offset:12288
	ds_read_b128 v[156:159], v196 offset:14336
	ds_read_b128 v[176:179], v243 offset:0
	ds_read_b128 v[180:183], v243 offset:2048
	ds_read_b128 v[184:187], v243 offset:4096
	ds_read_b128 v[188:191], v243 offset:6144
	ds_read_b128 v[204:207], v197 offset:0
	ds_read_b128 v[208:211], v197 offset:2048
	ds_read_b128 v[212:215], v197 offset:4096
	ds_read_b128 v[216:219], v197 offset:6144
	ds_read_b128 v[220:223], v197 offset:8192
	ds_read_b128 v[224:227], v197 offset:10240
	ds_read_b128 v[228:231], v197 offset:12288
	ds_read_b128 v[232:235], v197 offset:14336
	s_waitcnt lgkmcnt(12)
	s_setprio 1
	v_mfma_f32_16x16x32_bf16 v[0:3], v[160:163], v[128:131], v[0:3]
	v_mfma_f32_16x16x32_bf16 v[4:7], v[164:167], v[128:131], v[4:7]
	v_mfma_f32_16x16x32_bf16 v[8:11], v[168:171], v[128:131], v[8:11]
	v_mfma_f32_16x16x32_bf16 v[12:15], v[172:175], v[128:131], v[12:15]
	v_mfma_f32_16x16x32_bf16 v[16:19], v[160:163], v[132:135], v[16:19]
	v_mfma_f32_16x16x32_bf16 v[20:23], v[164:167], v[132:135], v[20:23]
	v_mfma_f32_16x16x32_bf16 v[24:27], v[168:171], v[132:135], v[24:27]
	v_mfma_f32_16x16x32_bf16 v[28:31], v[172:175], v[132:135], v[28:31]
	v_mfma_f32_16x16x32_bf16 v[32:35], v[160:163], v[136:139], v[32:35]
	v_mfma_f32_16x16x32_bf16 v[36:39], v[164:167], v[136:139], v[36:39]
	v_mfma_f32_16x16x32_bf16 v[40:43], v[168:171], v[136:139], v[40:43]
	v_mfma_f32_16x16x32_bf16 v[44:47], v[172:175], v[136:139], v[44:47]
	v_mfma_f32_16x16x32_bf16 v[48:51], v[160:163], v[140:143], v[48:51]
	v_mfma_f32_16x16x32_bf16 v[52:55], v[164:167], v[140:143], v[52:55]
	v_mfma_f32_16x16x32_bf16 v[56:59], v[168:171], v[140:143], v[56:59]
	v_mfma_f32_16x16x32_bf16 v[60:63], v[172:175], v[140:143], v[60:63]
	v_mfma_f32_16x16x32_bf16 v[64:67], v[160:163], v[144:147], v[64:67]
	v_mfma_f32_16x16x32_bf16 v[68:71], v[164:167], v[144:147], v[68:71]
	v_mfma_f32_16x16x32_bf16 v[72:75], v[168:171], v[144:147], v[72:75]
	v_mfma_f32_16x16x32_bf16 v[76:79], v[172:175], v[144:147], v[76:79]
	v_mfma_f32_16x16x32_bf16 v[80:83], v[160:163], v[148:151], v[80:83]
	v_mfma_f32_16x16x32_bf16 v[84:87], v[164:167], v[148:151], v[84:87]
	v_mfma_f32_16x16x32_bf16 v[88:91], v[168:171], v[148:151], v[88:91]
	v_mfma_f32_16x16x32_bf16 v[92:95], v[172:175], v[148:151], v[92:95]
	v_mfma_f32_16x16x32_bf16 v[96:99], v[160:163], v[152:155], v[96:99]
	v_mfma_f32_16x16x32_bf16 v[100:103], v[164:167], v[152:155], v[100:103]
	v_mfma_f32_16x16x32_bf16 v[104:107], v[168:171], v[152:155], v[104:107]
	v_mfma_f32_16x16x32_bf16 v[108:111], v[172:175], v[152:155], v[108:111]
	v_mfma_f32_16x16x32_bf16 v[112:115], v[160:163], v[156:159], v[112:115]
	v_mfma_f32_16x16x32_bf16 v[116:119], v[164:167], v[156:159], v[116:119]
	v_mfma_f32_16x16x32_bf16 v[120:123], v[168:171], v[156:159], v[120:123]
	v_mfma_f32_16x16x32_bf16 v[124:127], v[172:175], v[156:159], v[124:127]
	s_setprio 0
	s_waitcnt lgkmcnt(0)
	s_cmp_ge_u32 s91, 0x400
	s_cbranch_scc1 .Lq10_nonext
	s_barrier
	s_mov_b64 s[36:37], s[46:47]
	s_mov_b64 s[44:45], s[48:49]
	s_add_u32 s40, s36, 0x80000
	s_addc_u32 s41, s37, 0
	s_mov_b32 s20, s21
	s_add_u32 m0, s32, 0x0
	s_nop 0
	global_load_lds_dwordx4 v192, s[36:37]
	s_add_u32 m0, s32, 0x1000
	s_nop 0
	global_load_lds_dwordx4 v193, s[36:37]
	s_add_u32 m0, s32, 0x2000
	s_nop 0
	global_load_lds_dwordx4 v194, s[36:37]
	s_add_u32 m0, s32, 0x3000
	s_nop 0
	global_load_lds_dwordx4 v195, s[36:37]
	s_add_u32 m0, s32, 0x4000
	s_nop 0
	global_load_lds_dwordx4 v192, s[40:41]
	s_add_u32 m0, s32, 0x5000
	s_nop 0
	global_load_lds_dwordx4 v193, s[40:41]
	s_add_u32 m0, s32, 0x6000
	s_nop 0
	global_load_lds_dwordx4 v194, s[40:41]
	s_add_u32 m0, s32, 0x7000
	s_nop 0
	global_load_lds_dwordx4 v195, s[40:41]
	s_add_u32 m0, s32, 0x8000
	s_nop 0
	global_load_lds_dwordx4 v192, s[44:45]
	s_add_u32 m0, s32, 0x9000
	s_nop 0
	global_load_lds_dwordx4 v193, s[44:45]
	s_add_u32 m0, s32, 0xa000
	s_nop 0
	global_load_lds_dwordx4 v194, s[44:45]
	s_add_u32 m0, s32, 0xb000
	s_nop 0
	global_load_lds_dwordx4 v195, s[44:45]
	s_add_u32 s36, s36, 0x80
	s_addc_u32 s37, s37, 0
	s_add_u32 s40, s40, 0x80
	s_addc_u32 s41, s41, 0
	s_add_u32 s44, s44, 0x80
	s_addc_u32 s45, s45, 0
	s_add_i32 s20, s20, 1
	s_cmp_eq_u32 s20, 32
	s_cbranch_scc1 .Lq10_wrap2
.Lq10_wrapret2:
.Lq10_nonext:
	s_setprio 1
	v_mfma_f32_16x16x32_bf16 v[0:3], v[176:179], v[204:207], v[0:3]
	v_mfma_f32_16x16x32_bf16 v[4:7], v[180:183], v[204:207], v[4:7]
	v_mfma_f32_16x16x32_bf16 v[8:11], v[184:187], v[204:207], v[8:11]
	v_mfma_f32_16x16x32_bf16 v[12:15], v[188:191], v[204:207], v[12:15]
	v_mfma_f32_16x16x32_bf16 v[16:19], v[176:179], v[208:211], v[16:19]
	v_mfma_f32_16x16x32_bf16 v[20:23], v[180:183], v[208:211], v[20:23]
	v_mfma_f32_16x16x32_bf16 v[24:27], v[184:187], v[208:211], v[24:27]
	v_mfma_f32_16x16x32_bf16 v[28:31], v[188:191], v[208:211], v[28:31]
	v_mfma_f32_16x16x32_bf16 v[32:35], v[176:179], v[212:215], v[32:35]
	v_mfma_f32_16x16x32_bf16 v[36:39], v[180:183], v[212:215], v[36:39]
	v_mfma_f32_16x16x32_bf16 v[40:43], v[184:187], v[212:215], v[40:43]
	v_mfma_f32_16x16x32_bf16 v[44:47], v[188:191], v[212:215], v[44:47]
	v_mfma_f32_16x16x32_bf16 v[48:51], v[176:179], v[216:219], v[48:51]
	v_mfma_f32_16x16x32_bf16 v[52:55], v[180:183], v[216:219], v[52:55]
	v_mfma_f32_16x16x32_bf16 v[56:59], v[184:187], v[216:219], v[56:59]
	v_mfma_f32_16x16x32_bf16 v[60:63], v[188:191], v[216:219], v[60:63]
	v_mfma_f32_16x16x32_bf16 v[64:67], v[176:179], v[220:223], v[64:67]
	v_mfma_f32_16x16x32_bf16 v[68:71], v[180:183], v[220:223], v[68:71]
	v_mfma_f32_16x16x32_bf16 v[72:75], v[184:187], v[220:223], v[72:75]
	v_mfma_f32_16x16x32_bf16 v[76:79], v[188:191], v[220:223], v[76:79]
	v_mfma_f32_16x16x32_bf16 v[80:83], v[176:179], v[224:227], v[80:83]
	v_mfma_f32_16x16x32_bf16 v[84:87], v[180:183], v[224:227], v[84:87]
	v_mfma_f32_16x16x32_bf16 v[88:91], v[184:187], v[224:227], v[88:91]
	v_mfma_f32_16x16x32_bf16 v[92:95], v[188:191], v[224:227], v[92:95]
	v_mfma_f32_16x16x32_bf16 v[96:99], v[176:179], v[228:231], v[96:99]
	v_mfma_f32_16x16x32_bf16 v[100:103], v[180:183], v[228:231], v[100:103]
	v_mfma_f32_16x16x32_bf16 v[104:107], v[184:187], v[228:231], v[104:107]
	v_mfma_f32_16x16x32_bf16 v[108:111], v[188:191], v[228:231], v[108:111]
	v_mfma_f32_16x16x32_bf16 v[112:115], v[176:179], v[232:235], v[112:115]
	v_mfma_f32_16x16x32_bf16 v[116:119], v[180:183], v[232:235], v[116:119]
	v_mfma_f32_16x16x32_bf16 v[120:123], v[184:187], v[232:235], v[120:123]
	v_mfma_f32_16x16x32_bf16 v[124:127], v[188:191], v[232:235], v[124:127]
	s_setprio 0
	s_nop 7
	s_and_b32 s51, s90, 63
	s_lshl_b32 s51, s51, 21
	s_lshr_b32 s17, s90, 6
	s_lshl_b32 s17, s17, 9
	s_add_u32 s51, s51, s17
	s_add_u32 s14, s76, s51
	s_addc_u32 s15, s77, 0
	s_add_u32 s16, s92, s51
	s_addc_u32 s17, s93, 0
	s_mov_b32 s18, 0x3f9837f0
	v_lshrrev_b32_e32 v203, 7, v199
	v_and_b32_e32 v238, 15, v199
	v_lshl_add_u32 v203, v203, 7, v238
	v_lshlrev_b32_e32 v203, 13, v203
	v_bfe_u32 v238, v199, 6, 1
	v_lshl_add_u32 v203, v238, 8, v203
	v_bfe_u32 v238, v199, 4, 2
	v_lshl_add_u32 v203, v238, 4, v203
	global_load_dwordx4 v[128:131], v203, s[14:15] offset:0
	global_load_dwordx4 v[132:135], v203, s[14:15] offset:64
	global_load_dwordx4 v[136:139], v203, s[14:15] offset:128
	global_load_dwordx4 v[140:143], v203, s[14:15] offset:192
	s_add_u32 s14, s14, 0x20000
	s_addc_u32 s15, s15, 0
	global_load_dwordx4 v[144:147], v203, s[14:15] offset:0
	global_load_dwordx4 v[148:151], v203, s[14:15] offset:64
	global_load_dwordx4 v[152:155], v203, s[14:15] offset:128
	global_load_dwordx4 v[156:159], v203, s[14:15] offset:192
	s_add_u32 s14, s14, 0x20000
	s_addc_u32 s15, s15, 0
	s_waitcnt vmcnt(4)
	v_fma_f32 v128, s18, v128, v0
	v_fma_f32 v129, s18, v129, v1
	v_fma_f32 v130, s18, v130, v2
	v_fma_f32 v131, s18, v131, v3
	v_fma_f32 v132, s18, v132, v4
	v_fma_f32 v133, s18, v133, v5
	v_fma_f32 v134, s18, v134, v6
	v_fma_f32 v135, s18, v135, v7
	v_fma_f32 v136, s18, v136, v8
	v_fma_f32 v137, s18, v137, v9
	v_fma_f32 v138, s18, v138, v10
	v_fma_f32 v139, s18, v139, v11
	v_fma_f32 v140, s18, v140, v12
	v_fma_f32 v141, s18, v141, v13
	v_fma_f32 v142, s18, v142, v14
	v_fma_f32 v143, s18, v143, v15
	global_store_dwordx4 v203, v[128:131], s[16:17] offset:0
	global_store_dwordx4 v203, v[132:135], s[16:17] offset:64
	global_store_dwordx4 v203, v[136:139], s[16:17] offset:128
	global_store_dwordx4 v203, v[140:143], s[16:17] offset:192
	s_add_u32 s16, s16, 0x20000
	s_addc_u32 s17, s17, 0
	global_load_dwordx4 v[128:131], v203, s[14:15] offset:0
	global_load_dwordx4 v[132:135], v203, s[14:15] offset:64
	global_load_dwordx4 v[136:139], v203, s[14:15] offset:128
	global_load_dwordx4 v[140:143], v203, s[14:15] offset:192
	s_add_u32 s14, s14, 0x20000
	s_addc_u32 s15, s15, 0
	s_waitcnt vmcnt(8)
	v_fma_f32 v144, s18, v144, v16
	v_fma_f32 v145, s18, v145, v17
	v_fma_f32 v146, s18, v146, v18
	v_fma_f32 v147, s18, v147, v19
	v_fma_f32 v148, s18, v148, v20
	v_fma_f32 v149, s18, v149, v21
	v_fma_f32 v150, s18, v150, v22
	v_fma_f32 v151, s18, v151, v23
	v_fma_f32 v152, s18, v152, v24
	v_fma_f32 v153, s18, v153, v25
	v_fma_f32 v154, s18, v154, v26
	v_fma_f32 v155, s18, v155, v27
	v_fma_f32 v156, s18, v156, v28
	v_fma_f32 v157, s18, v157, v29
	v_fma_f32 v158, s18, v158, v30
	v_fma_f32 v159, s18, v159, v31
	global_store_dwordx4 v203, v[144:147], s[16:17] offset:0
	global_store_dwordx4 v203, v[148:151], s[16:17] offset:64
	global_store_dwordx4 v203, v[152:155], s[16:17] offset:128
	global_store_dwordx4 v203, v[156:159], s[16:17] offset:192
	s_add_u32 s16, s16, 0x20000
	s_addc_u32 s17, s17, 0
	global_load_dwordx4 v[144:147], v203, s[14:15] offset:0
	global_load_dwordx4 v[148:151], v203, s[14:15] offset:64
	global_load_dwordx4 v[152:155], v203, s[14:15] offset:128
	global_load_dwordx4 v[156:159], v203, s[14:15] offset:192
	s_add_u32 s14, s14, 0x20000
	s_addc_u32 s15, s15, 0
	s_waitcnt vmcnt(8)
	v_fma_f32 v128, s18, v128, v32
	v_fma_f32 v129, s18, v129, v33
	v_fma_f32 v130, s18, v130, v34
	v_fma_f32 v131, s18, v131, v35
	v_fma_f32 v132, s18, v132, v36
	v_fma_f32 v133, s18, v133, v37
	v_fma_f32 v134, s18, v134, v38
	v_fma_f32 v135, s18, v135, v39
	v_fma_f32 v136, s18, v136, v40
	v_fma_f32 v137, s18, v137, v41
	v_fma_f32 v138, s18, v138, v42
	v_fma_f32 v139, s18, v139, v43
	v_fma_f32 v140, s18, v140, v44
	v_fma_f32 v141, s18, v141, v45
	v_fma_f32 v142, s18, v142, v46
	v_fma_f32 v143, s18, v143, v47
	global_store_dwordx4 v203, v[128:131], s[16:17] offset:0
	global_store_dwordx4 v203, v[132:135], s[16:17] offset:64
	global_store_dwordx4 v203, v[136:139], s[16:17] offset:128
	global_store_dwordx4 v203, v[140:143], s[16:17] offset:192
	s_add_u32 s16, s16, 0x20000
	s_addc_u32 s17, s17, 0
	global_load_dwordx4 v[128:131], v203, s[14:15] offset:0
	global_load_dwordx4 v[132:135], v203, s[14:15] offset:64
	global_load_dwordx4 v[136:139], v203, s[14:15] offset:128
	global_load_dwordx4 v[140:143], v203, s[14:15] offset:192
	s_add_u32 s14, s14, 0x20000
	s_addc_u32 s15, s15, 0
	s_waitcnt vmcnt(8)
	v_fma_f32 v144, s18, v144, v48
	v_fma_f32 v145, s18, v145, v49
	v_fma_f32 v146, s18, v146, v50
	v_fma_f32 v147, s18, v147, v51
	v_fma_f32 v148, s18, v148, v52
	v_fma_f32 v149, s18, v149, v53
	v_fma_f32 v150, s18, v150, v54
	v_fma_f32 v151, s18, v151, v55
	v_fma_f32 v152, s18, v152, v56
	v_fma_f32 v153, s18, v153, v57
	v_fma_f32 v154, s18, v154, v58
	v_fma_f32 v155, s18, v155, v59
	v_fma_f32 v156, s18, v156, v60
	v_fma_f32 v157, s18, v157, v61
	v_fma_f32 v158, s18, v158, v62
	v_fma_f32 v159, s18, v159, v63
	global_store_dwordx4 v203, v[144:147], s[16:17] offset:0
	global_store_dwordx4 v203, v[148:151], s[16:17] offset:64
	global_store_dwordx4 v203, v[152:155], s[16:17] offset:128
	global_store_dwordx4 v203, v[156:159], s[16:17] offset:192
	s_add_u32 s16, s16, 0x20000
	s_addc_u32 s17, s17, 0
	global_load_dwordx4 v[144:147], v203, s[14:15] offset:0
	global_load_dwordx4 v[148:151], v203, s[14:15] offset:64
	global_load_dwordx4 v[152:155], v203, s[14:15] offset:128
	global_load_dwordx4 v[156:159], v203, s[14:15] offset:192
	s_add_u32 s14, s14, 0x20000
	s_addc_u32 s15, s15, 0
	s_waitcnt vmcnt(8)
	v_fma_f32 v128, s18, v128, v64
	v_fma_f32 v129, s18, v129, v65
	v_fma_f32 v130, s18, v130, v66
	v_fma_f32 v131, s18, v131, v67
	v_fma_f32 v132, s18, v132, v68
	v_fma_f32 v133, s18, v133, v69
	v_fma_f32 v134, s18, v134, v70
	v_fma_f32 v135, s18, v135, v71
	v_fma_f32 v136, s18, v136, v72
	v_fma_f32 v137, s18, v137, v73
	v_fma_f32 v138, s18, v138, v74
	v_fma_f32 v139, s18, v139, v75
	v_fma_f32 v140, s18, v140, v76
	v_fma_f32 v141, s18, v141, v77
	v_fma_f32 v142, s18, v142, v78
	v_fma_f32 v143, s18, v143, v79
	global_store_dwordx4 v203, v[128:131], s[16:17] offset:0
	global_store_dwordx4 v203, v[132:135], s[16:17] offset:64
	global_store_dwordx4 v203, v[136:139], s[16:17] offset:128
	global_store_dwordx4 v203, v[140:143], s[16:17] offset:192
	s_add_u32 s16, s16, 0x20000
	s_addc_u32 s17, s17, 0
	global_load_dwordx4 v[128:131], v203, s[14:15] offset:0
	global_load_dwordx4 v[132:135], v203, s[14:15] offset:64
	global_load_dwordx4 v[136:139], v203, s[14:15] offset:128
	global_load_dwordx4 v[140:143], v203, s[14:15] offset:192
	s_add_u32 s14, s14, 0x20000
	s_addc_u32 s15, s15, 0
	s_waitcnt vmcnt(8)
	v_fma_f32 v144, s18, v144, v80
	v_fma_f32 v145, s18, v145, v81
	v_fma_f32 v146, s18, v146, v82
	v_fma_f32 v147, s18, v147, v83
	v_fma_f32 v148, s18, v148, v84
	v_fma_f32 v149, s18, v149, v85
	v_fma_f32 v150, s18, v150, v86
	v_fma_f32 v151, s18, v151, v87
	v_fma_f32 v152, s18, v152, v88
	v_fma_f32 v153, s18, v153, v89
	v_fma_f32 v154, s18, v154, v90
	v_fma_f32 v155, s18, v155, v91
	v_fma_f32 v156, s18, v156, v92
	v_fma_f32 v157, s18, v157, v93
	v_fma_f32 v158, s18, v158, v94
	v_fma_f32 v159, s18, v159, v95
	global_store_dwordx4 v203, v[144:147], s[16:17] offset:0
	global_store_dwordx4 v203, v[148:151], s[16:17] offset:64
	global_store_dwordx4 v203, v[152:155], s[16:17] offset:128
	global_store_dwordx4 v203, v[156:159], s[16:17] offset:192
	s_add_u32 s16, s16, 0x20000
	s_addc_u32 s17, s17, 0
	global_load_dwordx4 v[144:147], v203, s[14:15] offset:0
	global_load_dwordx4 v[148:151], v203, s[14:15] offset:64
	global_load_dwordx4 v[152:155], v203, s[14:15] offset:128
	global_load_dwordx4 v[156:159], v203, s[14:15] offset:192
	s_add_u32 s14, s14, 0x20000
	s_addc_u32 s15, s15, 0
	s_waitcnt vmcnt(8)
	v_fma_f32 v128, s18, v128, v96
	v_fma_f32 v129, s18, v129, v97
	v_fma_f32 v130, s18, v130, v98
	v_fma_f32 v131, s18, v131, v99
	v_fma_f32 v132, s18, v132, v100
	v_fma_f32 v133, s18, v133, v101
	v_fma_f32 v134, s18, v134, v102
	v_fma_f32 v135, s18, v135, v103
	v_fma_f32 v136, s18, v136, v104
	v_fma_f32 v137, s18, v137, v105
	v_fma_f32 v138, s18, v138, v106
	v_fma_f32 v139, s18, v139, v107
	v_fma_f32 v140, s18, v140, v108
	v_fma_f32 v141, s18, v141, v109
	v_fma_f32 v142, s18, v142, v110
	v_fma_f32 v143, s18, v143, v111
	global_store_dwordx4 v203, v[128:131], s[16:17] offset:0
	global_store_dwordx4 v203, v[132:135], s[16:17] offset:64
	global_store_dwordx4 v203, v[136:139], s[16:17] offset:128
	global_store_dwordx4 v203, v[140:143], s[16:17] offset:192
	s_add_u32 s16, s16, 0x20000
	s_addc_u32 s17, s17, 0
	s_waitcnt vmcnt(4)
	v_fma_f32 v144, s18, v144, v112
	v_fma_f32 v145, s18, v145, v113
	v_fma_f32 v146, s18, v146, v114
	v_fma_f32 v147, s18, v147, v115
	v_fma_f32 v148, s18, v148, v116
	v_fma_f32 v149, s18, v149, v117
	v_fma_f32 v150, s18, v150, v118
	v_fma_f32 v151, s18, v151, v119
	v_fma_f32 v152, s18, v152, v120
	v_fma_f32 v153, s18, v153, v121
	v_fma_f32 v154, s18, v154, v122
	v_fma_f32 v155, s18, v155, v123
	v_fma_f32 v156, s18, v156, v124
	v_fma_f32 v157, s18, v157, v125
	v_fma_f32 v158, s18, v158, v126
	v_fma_f32 v159, s18, v159, v127
	global_store_dwordx4 v203, v[144:147], s[16:17] offset:0
	global_store_dwordx4 v203, v[148:151], s[16:17] offset:64
	global_store_dwordx4 v203, v[152:155], s[16:17] offset:128
	global_store_dwordx4 v203, v[156:159], s[16:17] offset:192
	s_add_u32 s16, s16, 0x20000
	s_addc_u32 s17, s17, 0
	s_add_u32 s90, s90, 0x200
	s_cmp_lt_u32 s90, 0x400
	s_cbranch_scc1 .Lq10_tile
	s_waitcnt vmcnt(0)
	s_mov_b32 s91, 1
	s_branch .Lq10_skip

.Lq10_skip:
	s_lshr_b32 s0, s96, 1
	s_cmp_ge_u32 s58, s0
	s_cselect_b64 s[6:7], -1, 0
	s_cmp_lt_u32 s58, s0
	s_cselect_b64 s[0:1], -1, 0
	s_cmp_eq_u32 s91, 1
	s_cselect_b32 s56, 0, 0x800
	s_cmp_lt_i32 s58, s56
	s_cselect_b64 s[8:9], -1, 0
	s_add_u32 s10, s94, 0x1c200000
	v_readlane_b32 s2, v242, 47
	s_addc_u32 s11, s95, 0
	s_and_b32 s2, s2, 0x700
	s_ashr_i32 s12, s58, 3
	s_add_i32 s2, s2, s12
	s_ashr_i32 s12, s2, 31
	s_lshr_b32 s12, s12, 25
	s_add_i32 s12, s2, s12
	s_and_b32 s13, s12, 0xffffff80
	s_sub_i32 s2, s2, s13
	s_bfe_i32 s13, s2, 0x80000
	s_bfe_u32 s13, s13, 0x3000c
	s_add_i32 s13, s2, s13
	s_bfe_i32 s14, s13, 0x80000
	s_and_b32 s13, s13, 0xf8
	s_sub_i32 s2, s2, s13
	s_sext_i32_i8 s2, s2
	s_sext_i32_i16 s14, s14
	s_lshl_b32 s33, s2, 7
	s_lshl_b32 s2, s12, 3
	s_lshl_b32 s14, s14, 4
	s_and_b32 s2, s2, 0xfffffc00
	v_mov_b32_e32 v70, 0x200
	v_mov_b32_e32 v2, 0x800
	s_and_b32 s23, s14, 0xffffff80
	s_add_i32 s33, s33, s2
	s_mov_b64 s[12:13], -1
	v_mov_b32_e32 v69, 0
	s_mov_b32 s2, 0x100000
	s_movk_i32 s38, 0x84
	s_mov_b64 s[14:15], 0x60000
	s_mov_b64 s[16:17], 0x40000
	s_mov_b64 s[18:19], 0x20000
	s_movk_i32 s39, 0xffc0
	s_mov_b32 s42, 0x1ffffc0
	s_mov_b64 s[20:21], 0x80
	s_mov_b32 s22, 0x3f9837f0
	v_mov_b32_e32 v0, 0x200
	v_mov_b32_e32 v1, v70
	v_mov_b32_e32 v3, v2
	v_mov_b32_e32 v71, 32
	v_mov_b32_e32 v72, 0x2000
	s_branch .LBB0_765
